# half of the workgroups (blockIdx bit 3) start P1 12us / P6 16us late so epilogue bursts of the two groups do not coincide
# baseline (speedup 1.0000x reference)
; #define LAS __attribute__((address_space(3)))
; __device__ __forceinline__ unsigned xb_add(unsigned* p, unsigned v) { return __hip_atomic_fetch_add(p, v, __ATOMIC_RELAXED, __HIP_MEMORY_SCOPE_AGENT); }
; __device__ __forceinline__ unsigned xb_xcc_id() { return (unsigned)__builtin_amdgcn_s_getreg((3 << 11) | 20) & 0xFu; }
; __device__ __forceinline__ XcdBarrier xcd_barrier_post(unsigned* bar, volatile LAS unsigned* st) {
;     XcdBarrier b; b.bar = bar; b.x = xb_xcc_id(); b.st = st;
;     if (threadIdx.x == 0) (void)xb_add(&bar[XB_XCNT(b.x)], 1u);
;     return b;
; }
; __global__ void __launch_bounds__(512) mega_fwd(Args a_unused) {
;     ...
;     grid.sync();
;     const XcdBarrier xbar = xcd_barrier_post((unsigned*)(kp->ws + S_BAR), bst);
.LBB0_203:
	s_or_b64 exec, exec, s[4:5]
	s_barrier
	s_bitcmp1_b32 s3, 3
	s_cbranch_scc0 .Lstg_skip_0
	s_memrealtime s[98:99]
	s_waitcnt lgkmcnt(0)
	s_add_u32 s98, s98, 1200
.Lstg_spin_0:
	s_sleep 8
	s_memrealtime s[100:101]
	s_waitcnt lgkmcnt(0)
	s_sub_u32 s100, s100, s98
	s_cmp_lt_i32 s100, 0
	s_cbranch_scc1 .Lstg_spin_0
.Lstg_skip_0:
	s_load_dwordx2 s[6:7], s[0:1], 0xe8
	s_getreg_b32 s4, hwreg(HW_REG_XCC_ID, 0, 4)
	s_waitcnt lgkmcnt(0)
	s_add_u32 s8, s6, 0x2700000
	v_writelane_b32 v253, s6, 1
	s_addc_u32 s9, s7, 0
	s_and_b32 s4, s4, 15
	v_writelane_b32 v253, s7, 2
	v_writelane_b32 v253, s8, 3
	s_nop 1
	v_writelane_b32 v253, s9, 4
	v_writelane_b32 v253, s4, 5
	s_and_saveexec_b64 s[4:5], s[76:77]
	s_cbranch_execz .LBB0_206
	s_mov_b64 s[6:7], exec
	v_mbcnt_lo_u32_b32 v0, s6, 0
	v_mbcnt_hi_u32_b32 v0, s7, v0
	v_cmp_eq_u32_e32 vcc, 0, v0
	s_and_b64 s[8:9], exec, vcc
	s_mov_b64 exec, s[8:9]
	s_cbranch_execz .LBB0_206
	v_readlane_b32 s8, v253, 5
	s_bcnt1_i32_b64 s6, s[6:7]
	s_lshl_b32 s8, s8, 8
	v_mov_b32_e32 v1, s6
	v_readlane_b32 s6, v253, 3
	v_mov_b32_e32 v0, s8
	v_readlane_b32 s7, v253, 4
	s_nop 4
	global_atomic_add v0, v1, s[6:7] offset:1024

; #define FRESH() asm volatile("" : "+s"(kp))
; __global__ void __launch_bounds__(512) mega_fwd(Args a_unused) {
;     ...
;     xcd_barrier(xbar);
; #pragma unroll 1
;     for (int rep6 = 0; rep6 < REP_P6; ++rep6) { FRESH(); const Bag b = make_bag(kp, lds); pg8::Gemm g{b.x1b, WSP(W_FF1), T, 4096, 1024, 1024}; pg8::StaticOrder S; S.init(T, 4096, G, bid); Epi<K_FF1> E{b, 0}; pg8::gemm_phase<Epi<K_FF1>, pg8::StaticOrder, true, true, 1024, 1024>(lds, g, S, E); }
.LBB0_1328:
	s_or_b64 exec, exec, s[0:1]
	v_mov_b32_e32 v8, v232
	s_waitcnt lgkmcnt(0)
	s_barrier
	s_bitcmp1_b32 s3, 3
	s_cbranch_scc0 .Lstg_skip_1
	s_memrealtime s[98:99]
	s_waitcnt lgkmcnt(0)
	s_add_u32 s98, s98, 1600

; #define PG8_STAGE(bufoff, gbase, voff) do { _Pragma("unroll") for (int _i = 0; _i < 2; ++_i) \
;         __builtin_amdgcn_global_load_lds((const unsigned*)((const char*)(gbase) + (voff)[_i]), (PG8_LAS unsigned*)(lds + (bufoff) + ldsw + _i * 8192), 16, 0, 0); } while (0)
; #define PG8_BAR __builtin_amdgcn_s_barrier()
;     ...
;     const int tid = tid_, wid = __builtin_amdgcn_readfirstlane(tid >> 6), lane = tid & 63, wr = wid >> 2, wc = wid & 3, fr = lane & 15, fq = lane >> 4;
;     const int K = KC ? KC : g.K, nt = K / BK, lda_ = LDAC ? LDAC : g.lda;
;     unsigned voffA[2], voffB[2];
; #pragma unroll
;     for (int i = 0; i < 2; ++i) { int R, C; stage_rc(tid * 16 + i * 8192, R, C); const int Rb = Epi::PERM ? ((R & ~31) + perm32(R & 31)) : R;
;         voffA[i] = (unsigned)(R * lda_ + C) * 2u; voffB[i] = (unsigned)(Rb * K + C) * 2u; }
;     const size_t kstep = (size_t)(BK * 2);
;     const size_t hstepA = (size_t)HALF * lda_ * 2, hstepB = (size_t)HALF * K * 2;
;     const size_t tstepA = 2 * hstepA, tstepB = 2 * hstepB;
;     const unsigned ldsw = (unsigned)wid * 1024u;
;     const int aoff = lds_byte(wr * 64 + fr, fq * 8), boff = lds_byte(wc * 32 + fr, fq * 8);
;     ...
;     const char* cA = (const char*)g.A + (size_t)cur.pm * tstepA; const char* cB = (const char*)g.Bt + (size_t)cur.pn * tstepB;
;     S.a_ready(cur);
;     if constexpr (SP2) {
;         PG8_STAGE(PG8_SB(0, 0), cB, voffB); PG8_STAGE(PG8_SB(0, 1), cB + hstepB, voffB); PG8_STAGE(PG8_SA(0, 0), cA, voffA); PG8_STAGE(PG8_SA(0, 1), cA + hstepA, voffA);
;         if (wr == 1) PG8_BAR;
.Lstg_skip_1:
	s_cmpk_lt_i32 s3, 0x1000
	s_nop 0
	v_readfirstlane_b32 s17, v8
	s_cbranch_scc0 .LBB0_1348
	v_lshlrev_b32_e32 v0, 4, v8
	v_add_u32_e32 v1, 0x2000, v0
	v_ashrrev_i32_e32 v2, 31, v1
	v_lshrrev_b32_e32 v2, 22, v2
	v_add_u32_e32 v2, v1, v2
	v_ashrrev_i32_e32 v9, 10, v2
	v_mul_i32_i24_e32 v2, 0x400, v9
	v_sub_u32_e32 v1, v1, v2
	v_lshrrev_b32_e32 v2, 4, v1
	v_bitop3_b32 v1, v2, v1, 32 bitop3:0x6c
	v_ashrrev_i32_e32 v2, 31, v1
	v_lshrrev_b32_e32 v2, 26, v2
	v_add_u32_e32 v2, v1, v2
	v_lshlrev_b32_e32 v3, 3, v9
	v_ashrrev_i32_e32 v10, 6, v2
	v_and_b32_e32 v3, -16, v3
	v_add_u32_e32 v3, v10, v3
	v_and_b32_e32 v4, 3, v10
	s_mov_b32 s4, 0x1fffe0
	v_lshrrev_b32_e32 v5, 2, v3
	v_lshlrev_b32_e32 v6, 1, v3
	v_and_b32_e32 v2, 0xc0, v2
	v_and_or_b32 v4, v3, s4, v4
	v_and_b32_e32 v5, 4, v5
	v_and_b32_e32 v6, 24, v6
	v_sub_u32_e32 v1, v1, v2
	v_mov_b32_e32 v2, 1
	v_or3_b32 v4, v4, v5, v6
	v_lshlrev_b32_e32 v5, 5, v9
	v_ashrrev_i16_sdwa v1, v2, sext(v1) dst_sel:DWORD dst_unused:UNUSED_PAD src0_sel:DWORD src1_sel:BYTE_0
	v_and_b32_e32 v5, 32, v5
	v_bfe_i32 v11, v1, 0, 16
	v_add_lshl_u32 v1, v5, v11, 1
	v_lshl_add_u32 v128, v4, 11, v1
	v_lshl_add_u32 v130, v3, 11, v1
	v_bfe_i32 v1, v8, 27, 1
	v_lshrrev_b32_e32 v1, 22, v1
	v_add_u32_e32 v1, v0, v1
	v_and_b32_e32 v1, 0xfffffc00, v1
	v_sub_u32_e32 v0, v0, v1
	s_load_dwordx2 s[0:1], s[88:89], 0xe8
	v_lshrrev_b32_e32 v1, 4, v0
	v_ashrrev_i32_e32 v3, 31, v8
	v_bitop3_b32 v0, v1, v0, 32 bitop3:0x6c
	v_lshrrev_b32_e32 v3, 26, v3
	v_ashrrev_i32_e32 v1, 31, v0
	v_add_u32_e32 v3, v8, v3
	v_lshrrev_b32_e32 v1, 26, v1
	v_ashrrev_i32_e32 v13, 6, v3
	v_add_u32_e32 v1, v0, v1
	v_lshlrev_b32_e32 v3, 3, v13
	s_waitcnt lgkmcnt(0)
	s_add_u32 s15, s0, 0x4800000
	v_ashrrev_i32_e32 v12, 6, v1
	v_and_b32_e32 v3, -16, v3
	s_addc_u32 s40, s1, 0
	v_add_u32_e32 v3, v12, v3
	v_and_b32_e32 v4, 3, v12
	s_add_u32 s41, s0, 0x1600000
	v_and_or_b32 v4, v3, s4, v4
	v_readlane_b32 s4, v253, 9
	s_addc_u32 s42, s1, 0
	s_ashr_i32 s10, s17, 6
	s_mul_i32 s6, s4, 0x201
	s_lshl_b32 s7, s4, 9
	v_readlane_b32 s4, v253, 10
	s_ashr_i32 s11, s17, 8
	s_lshl_b32 s43, s10, 10
	v_readlane_b32 s5, v253, 11
	s_and_b64 s[4:5], s[4:5], exec
	s_cselect_b32 s4, s6, s7
	v_readlane_b32 s5, v253, 12
	s_add_i32 s4, s4, s5
	s_ashr_i32 s5, s4, 31
	s_lshr_b32 s5, s5, 25
	s_add_i32 s5, s4, s5
	s_ashr_i32 s6, s5, 7
	s_and_b32 s5, s5, 0xff80
	s_sub_i32 s4, s4, s5
	s_bfe_i32 s5, s4, 0x80000
	s_bfe_u32 s5, s5, 0x3000c
	s_add_i32 s5, s4, s5
	s_bfe_i32 s7, s5, 0x80000
	s_and_b32 s5, s5, 0xf8
	s_sub_i32 s4, s4, s5
	s_lshl_b32 s6, s6, 3
	s_sext_i32_i16 s7, s7
	s_sext_i32_i8 s4, s4
	v_lshrrev_b32_e32 v5, 2, v3
	v_lshlrev_b32_e32 v6, 1, v3
	v_and_b32_e32 v1, 0xc0, v1
	s_lshr_b32 s16, s7, 3
	s_add_i32 s28, s6, s4
	v_and_b32_e32 v5, 4, v5
	v_and_b32_e32 v6, 24, v6
	v_sub_u32_e32 v0, v0, v1
	s_ashr_i32 s29, s28, 31
	s_bfe_i64 s[6:7], s[16:17], 0x100000
	v_or3_b32 v4, v4, v5, v6
	v_lshlrev_b32_e32 v5, 5, v13
	v_ashrrev_i16_sdwa v0, v2, sext(v0) dst_sel:DWORD dst_unused:UNUSED_PAD src0_sel:DWORD src1_sel:BYTE_0
	s_lshl_b64 s[4:5], s[28:29], 19
	s_lshl_b64 s[6:7], s[6:7], 19
	v_and_b32_e32 v5, 32, v5
	v_bfe_i32 v14, v0, 0, 16
	s_add_u32 s36, s41, s6
	v_add_lshl_u32 v0, v5, v14, 1
	s_addc_u32 s37, s42, s7
	s_add_i32 s29, s43, 0
	v_lshl_add_u32 v132, v4, 11, v0
	s_add_i32 m0, s29, 0x10000
	v_lshl_add_u32 v134, v3, 11, v0
	global_load_lds_dwordx4 v132, s[36:37]
	s_add_i32 m0, s29, 0x12000
	s_add_u32 s6, s36, 0x40000
	global_load_lds_dwordx4 v128, s[36:37]
	s_addc_u32 s7, s37, 0
	s_add_i32 m0, s29, 0x14000
	v_mov_b32_e32 v133, 0
	global_load_lds_dwordx4 v132, s[6:7]
	s_add_i32 m0, s29, 0x16000
	s_add_u32 s34, s15, s4
	s_addc_u32 s35, s40, s5
	s_add_i32 s44, s29, 0x2000
	global_load_lds_dwordx4 v128, s[6:7]
	s_mov_b32 m0, s29
	s_add_u32 s4, s34, 0x40000
	global_load_lds_dwordx4 v134, s[34:35]
	s_mov_b32 m0, s44
	s_addc_u32 s5, s35, 0
	s_add_i32 s45, s29, 0x4000
	global_load_lds_dwordx4 v130, s[34:35]
	s_mov_b32 m0, s45
	s_add_i32 s46, s29, 0x6000
	global_load_lds_dwordx4 v134, s[4:5]
	s_mov_b32 m0, s46
	v_mov_b32_e32 v129, v133
	global_load_lds_dwordx4 v130, s[4:5]
	v_mov_b32_e32 v135, v133
	v_mov_b32_e32 v131, v133
	s_cmp_eq_u32 s11, 1
	s_mov_b32 s47, 0
	v_lshl_add_u64 v[6:7], s[36:37], 0, v[132:133]
	v_lshl_add_u64 v[4:5], s[36:37], 0, v[128:129]
	v_lshl_add_u64 v[0:1], s[34:35], 0, v[134:135]
	s_cselect_b64 s[4:5], -1, 0
	s_cmp_lg_u32 s11, 1
	v_lshl_add_u64 v[2:3], s[34:35], 0, v[130:131]
	s_cbranch_scc1 .LBB0_1331
	s_barrier

; __global__ void __launch_bounds__(512) mega_fwd(Args a_unused) {
	.amdhsa_kernel _Z8mega_fwd4Args
		.amdhsa_group_segment_fixed_size 0
		.amdhsa_private_segment_fixed_size 0
		.amdhsa_kernarg_size 496
		.amdhsa_user_sgpr_count 2
		.amdhsa_user_sgpr_dispatch_ptr 0
		.amdhsa_user_sgpr_queue_ptr 0
		.amdhsa_user_sgpr_kernarg_segment_ptr 1
		.amdhsa_user_sgpr_dispatch_id 0
		.amdhsa_user_sgpr_kernarg_preload_length 0
		.amdhsa_user_sgpr_kernarg_preload_offset 0
		.amdhsa_user_sgpr_private_segment_size 0
		.amdhsa_uses_dynamic_stack 0
		.amdhsa_enable_private_segment 0
		.amdhsa_system_sgpr_workgroup_id_x 1
		.amdhsa_system_sgpr_workgroup_id_y 0
		.amdhsa_system_sgpr_workgroup_id_z 0
		.amdhsa_system_sgpr_workgroup_info 0
		.amdhsa_system_vgpr_workitem_id 2
		.amdhsa_next_free_vgpr 254
		.amdhsa_next_free_sgpr 102
		.amdhsa_accum_offset 256
		.amdhsa_reserve_vcc 1
		.amdhsa_float_round_mode_32 0
		.amdhsa_float_round_mode_16_64 0
		.amdhsa_float_denorm_mode_32 3
		.amdhsa_float_denorm_mode_16_64 3
		.amdhsa_dx10_clamp 1
		.amdhsa_ieee_mode 1
		.amdhsa_fp16_overflow 0
		.amdhsa_tg_split 0
		.amdhsa_exception_fp_ieee_invalid_op 0
		.amdhsa_exception_fp_denorm_src 0
		.amdhsa_exception_fp_ieee_div_zero 0
		.amdhsa_exception_fp_ieee_overflow 0
		.amdhsa_exception_fp_ieee_underflow 0
		.amdhsa_exception_fp_ieee_inexact 0
		.amdhsa_exception_int_div_zero 0
	.end_amdhsa_kernel

; __global__ void __launch_bounds__(512) mega_fwd(Args a_unused) {
amdhsa.kernels:
  - .agpr_count:     0
    .args:
      - .offset:         0
        .size:           240
        .value_kind:     by_value
      - .offset:         240
        .size:           4
        .value_kind:     hidden_block_count_x
      - .offset:         244
        .size:           4
        .value_kind:     hidden_block_count_y
      - .offset:         248
        .size:           4
        .value_kind:     hidden_block_count_z
      - .offset:         252
        .size:           2
        .value_kind:     hidden_group_size_x
      - .offset:         254
        .size:           2
        .value_kind:     hidden_group_size_y
      - .offset:         256
        .size:           2
        .value_kind:     hidden_group_size_z
      - .offset:         258
        .size:           2
        .value_kind:     hidden_remainder_x
      - .offset:         260
        .size:           2
        .value_kind:     hidden_remainder_y
      - .offset:         262
        .size:           2
        .value_kind:     hidden_remainder_z
      - .offset:         280
        .size:           8
        .value_kind:     hidden_global_offset_x
      - .offset:         288
        .size:           8
        .value_kind:     hidden_global_offset_y
      - .offset:         296
        .size:           8
        .value_kind:     hidden_global_offset_z
      - .offset:         304
        .size:           2
        .value_kind:     hidden_grid_dims
      - .offset:         328
        .size:           8
        .value_kind:     hidden_multigrid_sync_arg
      - .offset:         360
        .size:           4
        .value_kind:     hidden_dynamic_lds_size
    .group_segment_fixed_size: 0
    .kernarg_segment_align: 8
    .kernarg_segment_size: 496
    .language:       OpenCL C
    .language_version:
      - 2
      - 0
    .max_flat_workgroup_size: 512
    .name:           _Z8mega_fwd4Args
    .private_segment_fixed_size: 0
    .sgpr_count:     108
    .sgpr_spill_count: 45
    .symbol:         _Z8mega_fwd4Args.kd
    .uniform_work_group_size: 1
    .uses_dynamic_stack: false
    .vgpr_count:     254
    .vgpr_spill_count: 0
    .wavefront_size: 64
